# GLU GEMM epilogue: 16-byte gate loads and MIX stores (n pairs merged), loads requested up front with counted waits
# speedup vs baseline: 1.0331x; 1.0130x over previous
; __device__ __forceinline__ unsigned cvt_pk_bf16(float lo, float hi) { unsigned r; asm volatile("v_cvt_pk_bf16_f32 %0, %1, %2" : "=v"(r) : "v"(lo), "v"(hi)); return r; }
; __device__ __forceinline__ float sigm(float v) { return __builtin_amdgcn_rcpf(1.0f + __builtin_amdgcn_exp2f(-1.4426950408889634f * v)); }
;     __device__ __forceinline__ void operator()(const f32x4 (&acc)[2][2][4][2], const Unit& u, int wr, int wc, int fr, int fq) const {
;         typedef unsigned u32x2 __attribute__((ext_vector_type(2)));
;         const int row0 = u.pm * BM + wr * 64 + fr, col0 = wc * 32 + 8 * fq;
; #pragma unroll
;         for (int bj = 0; bj < 2; ++bj)
; #pragma unroll
;             for (int n = 0; n < 2; ++n) {
;                 const int c = col0 + bj * HALF + 4 * n;
;                 const f32x4 bv = *(const f32x4*)(bias + c);
; #pragma unroll
;                 for (int ai = 0; ai < 2; ++ai)
; #pragma unroll
;                     for (int m = 0; m < 4; ++m) {
;                         const size_t row = (size_t)(row0 + ai * HALF + m * 16);
;                         const f32x4 v = acc[ai][bj][m][n] + bv;
;                         const u32x2 yv = *(const u32x2*)(YGS + row * 256 + c);
;                         const float y0 = __uint_as_float(yv.x << 16), y1 = __uint_as_float(yv.x & 0xffff0000u), y2 = __uint_as_float(yv.y << 16), y3 = __uint_as_float(yv.y & 0xffff0000u);
;                         u32x2 w; w.x = cvt_pk_bf16(y0 * sigm(v[0]), y1 * sigm(v[1])); w.y = cvt_pk_bf16(y2 * sigm(v[2]), y3 * sigm(v[3]));
;                         *(u32x2*)(MIX + row * 1024 + 256 + c) = w;
;                         if (m & 1) asm volatile("" ::: "memory");
;                     }
;             }
.LBB0_843:
	v_lshl_add_u32 v154, s54, 8, v156
	s_and_b64 vcc, exec, s[0:1]
	s_mov_b64 s[0:1], -1
	global_load_dwordx4 v[128:131], v[138:139], off
	global_load_dwordx4 v[208:211], v[138:139], off offset:16
	v_lshlrev_b32_e32 v220, 9, v154
	v_lshl_add_u64 v[148:149], v[140:141], 0, v[220:221]
	global_load_dwordx4 v[160:163], v[148:149], off
	v_or_b32_e32 v152, 16, v154
	v_lshlrev_b32_e32 v220, 9, v152
	v_lshl_add_u64 v[148:149], v[140:141], 0, v[220:221]
	global_load_dwordx4 v[164:167], v[148:149], off
	v_or_b32_e32 v152, 32, v154
	v_lshlrev_b32_e32 v220, 9, v152
	v_lshl_add_u64 v[148:149], v[140:141], 0, v[220:221]
	global_load_dwordx4 v[168:171], v[148:149], off
	v_or_b32_e32 v152, 48, v154
	v_lshlrev_b32_e32 v220, 9, v152
	v_lshl_add_u64 v[148:149], v[140:141], 0, v[220:221]
	global_load_dwordx4 v[172:175], v[148:149], off
	v_or_b32_e32 v152, 0x80, v154
	v_lshlrev_b32_e32 v220, 9, v152
	v_lshl_add_u64 v[148:149], v[140:141], 0, v[220:221]
	global_load_dwordx4 v[176:179], v[148:149], off
	v_or_b32_e32 v152, 0x90, v154
	v_lshlrev_b32_e32 v220, 9, v152
	v_lshl_add_u64 v[148:149], v[140:141], 0, v[220:221]
	global_load_dwordx4 v[180:183], v[148:149], off
	v_or_b32_e32 v152, 0xa0, v154
	v_lshlrev_b32_e32 v220, 9, v152
	v_lshl_add_u64 v[148:149], v[140:141], 0, v[220:221]
	global_load_dwordx4 v[184:187], v[148:149], off
	v_or_b32_e32 v152, 0xb0, v154
	v_lshlrev_b32_e32 v220, 9, v152
	v_lshl_add_u64 v[148:149], v[140:141], 0, v[220:221]
	global_load_dwordx4 v[188:191], v[148:149], off
	v_lshlrev_b32_e32 v220, 9, v154
	v_lshl_add_u64 v[148:149], v[140:141], 0, v[220:221]
	global_load_dwordx4 v[192:195], v[148:149], off offset:256
	v_or_b32_e32 v152, 16, v154
	v_lshlrev_b32_e32 v220, 9, v152
	v_lshl_add_u64 v[148:149], v[140:141], 0, v[220:221]
	global_load_dwordx4 v[196:199], v[148:149], off offset:256
	v_or_b32_e32 v152, 32, v154
	v_lshlrev_b32_e32 v220, 9, v152
	v_lshl_add_u64 v[148:149], v[140:141], 0, v[220:221]
	global_load_dwordx4 v[200:203], v[148:149], off offset:256
	v_or_b32_e32 v152, 48, v154
	v_lshlrev_b32_e32 v220, 9, v152
	v_lshl_add_u64 v[148:149], v[140:141], 0, v[220:221]
	global_load_dwordx4 v[204:207], v[148:149], off offset:256
	s_waitcnt vmcnt(11)
	v_pk_add_f32 v[124:125], v[124:125], v[128:129]
	v_pk_add_f32 v[126:127], v[126:127], v[130:131]
	v_pk_add_f32 v[92:93], v[92:93], v[208:209]
	v_pk_add_f32 v[94:95], v[94:95], v[210:211]
	v_mul_f32_e32 v124, 0xbfb8aa3b, v124
	v_mul_f32_e32 v125, 0xbfb8aa3b, v125
	v_mul_f32_e32 v126, 0xbfb8aa3b, v126
	v_mul_f32_e32 v127, 0xbfb8aa3b, v127
	v_mul_f32_e32 v92, 0xbfb8aa3b, v92
	v_mul_f32_e32 v93, 0xbfb8aa3b, v93
	v_mul_f32_e32 v94, 0xbfb8aa3b, v94
	v_mul_f32_e32 v95, 0xbfb8aa3b, v95
	v_exp_f32_e32 v124, v124
	v_exp_f32_e32 v125, v125
	v_exp_f32_e32 v126, v126
	v_exp_f32_e32 v127, v127
	v_exp_f32_e32 v92, v92
	v_exp_f32_e32 v93, v93
	v_exp_f32_e32 v94, v94
	v_exp_f32_e32 v95, v95
	v_add_f32_e32 v124, 1.0, v124
	v_add_f32_e32 v125, 1.0, v125
	v_add_f32_e32 v126, 1.0, v126
	v_add_f32_e32 v127, 1.0, v127
	v_add_f32_e32 v92, 1.0, v92
	v_add_f32_e32 v93, 1.0, v93
	v_add_f32_e32 v94, 1.0, v94
	v_add_f32_e32 v95, 1.0, v95
	v_rcp_f32_e32 v124, v124
	v_rcp_f32_e32 v125, v125
	v_rcp_f32_e32 v126, v126
	v_rcp_f32_e32 v127, v127
	v_rcp_f32_e32 v92, v92
	v_rcp_f32_e32 v93, v93
	v_rcp_f32_e32 v94, v94
	v_rcp_f32_e32 v95, v95
	v_lshlrev_b32_e32 v153, 16, v160
	v_and_b32_e32 v160, 0xffff0000, v160
	v_lshlrev_b32_e32 v155, 16, v161
	v_and_b32_e32 v161, 0xffff0000, v161
	v_mul_f32_e32 v124, v124, v153
	v_mul_f32_e32 v125, v125, v160
	v_mul_f32_e32 v126, v126, v155
	v_mul_f32_e32 v127, v127, v161
	v_lshlrev_b32_e32 v153, 16, v162
	v_and_b32_e32 v162, 0xffff0000, v162
	v_lshlrev_b32_e32 v155, 16, v163
	v_and_b32_e32 v163, 0xffff0000, v163
	v_mul_f32_e32 v92, v92, v153
	v_mul_f32_e32 v93, v93, v162
	v_mul_f32_e32 v94, v94, v155
	v_mul_f32_e32 v95, v95, v163
	v_cvt_pk_bf16_f32 v124, v124, v125
	v_cvt_pk_bf16_f32 v125, v126, v127
	v_cvt_pk_bf16_f32 v126, v92, v93
	v_cvt_pk_bf16_f32 v127, v94, v95
	v_lshlrev_b32_e32 v220, 11, v154
	v_lshl_add_u64 v[150:151], v[142:143], 0, v[220:221]
	global_store_dwordx4 v[150:151], v[124:127], off offset:512
	global_load_dwordx4 v[92:95], v[138:139], off offset:512
	s_waitcnt vmcnt(12)
	v_pk_add_f32 v[120:121], v[120:121], v[128:129]
	v_pk_add_f32 v[122:123], v[122:123], v[130:131]
	v_pk_add_f32 v[88:89], v[88:89], v[208:209]
	v_pk_add_f32 v[90:91], v[90:91], v[210:211]
	v_mul_f32_e32 v120, 0xbfb8aa3b, v120
	v_mul_f32_e32 v121, 0xbfb8aa3b, v121
	v_mul_f32_e32 v122, 0xbfb8aa3b, v122
	v_mul_f32_e32 v123, 0xbfb8aa3b, v123
	v_mul_f32_e32 v88, 0xbfb8aa3b, v88
	v_mul_f32_e32 v89, 0xbfb8aa3b, v89
	v_mul_f32_e32 v90, 0xbfb8aa3b, v90
	v_mul_f32_e32 v91, 0xbfb8aa3b, v91
	v_exp_f32_e32 v120, v120
	v_exp_f32_e32 v121, v121
	v_exp_f32_e32 v122, v122
	v_exp_f32_e32 v123, v123
	v_exp_f32_e32 v88, v88
	v_exp_f32_e32 v89, v89
	v_exp_f32_e32 v90, v90
	v_exp_f32_e32 v91, v91
	v_add_f32_e32 v120, 1.0, v120
	v_add_f32_e32 v121, 1.0, v121
	v_add_f32_e32 v122, 1.0, v122
	v_add_f32_e32 v123, 1.0, v123
	v_add_f32_e32 v88, 1.0, v88
	v_add_f32_e32 v89, 1.0, v89
	v_add_f32_e32 v90, 1.0, v90
	v_add_f32_e32 v91, 1.0, v91
	v_rcp_f32_e32 v120, v120
	v_rcp_f32_e32 v121, v121
	v_rcp_f32_e32 v122, v122
	v_rcp_f32_e32 v123, v123
	v_rcp_f32_e32 v88, v88
	v_rcp_f32_e32 v89, v89
	v_rcp_f32_e32 v90, v90
	v_rcp_f32_e32 v91, v91
	v_lshlrev_b32_e32 v153, 16, v164
	v_and_b32_e32 v164, 0xffff0000, v164
	v_lshlrev_b32_e32 v155, 16, v165
	v_and_b32_e32 v165, 0xffff0000, v165
	v_mul_f32_e32 v120, v120, v153
	v_mul_f32_e32 v121, v121, v164
	v_mul_f32_e32 v122, v122, v155
	v_mul_f32_e32 v123, v123, v165
	v_lshlrev_b32_e32 v153, 16, v166
	v_and_b32_e32 v166, 0xffff0000, v166
	v_lshlrev_b32_e32 v155, 16, v167
	v_and_b32_e32 v167, 0xffff0000, v167
	v_mul_f32_e32 v88, v88, v153
	v_mul_f32_e32 v89, v89, v166
	v_mul_f32_e32 v90, v90, v155
	v_mul_f32_e32 v91, v91, v167
	v_cvt_pk_bf16_f32 v120, v120, v121
	v_cvt_pk_bf16_f32 v121, v122, v123
	v_cvt_pk_bf16_f32 v122, v88, v89
	v_cvt_pk_bf16_f32 v123, v90, v91
	v_or_b32_e32 v152, 16, v154
	v_lshlrev_b32_e32 v220, 11, v152
	v_lshl_add_u64 v[150:151], v[142:143], 0, v[220:221]
	global_store_dwordx4 v[150:151], v[120:123], off offset:512
	global_load_dwordx4 v[88:91], v[138:139], off offset:528
	s_waitcnt vmcnt(13)
; __device__ __forceinline__ unsigned cvt_pk_bf16(float lo, float hi) { unsigned r; asm volatile("v_cvt_pk_bf16_f32 %0, %1, %2" : "=v"(r) : "v"(lo), "v"(hi)); return r; }
; __device__ __forceinline__ float sigm(float v) { return __builtin_amdgcn_rcpf(1.0f + __builtin_amdgcn_exp2f(-1.4426950408889634f * v)); }
;     __device__ __forceinline__ void operator()(const f32x4 (&acc)[2][2][4][2], const Unit& u, int wr, int wc, int fr, int fq) const {
;         typedef unsigned u32x2 __attribute__((ext_vector_type(2)));
;         const int row0 = u.pm * BM + wr * 64 + fr, col0 = wc * 32 + 8 * fq;
; #pragma unroll
;         for (int bj = 0; bj < 2; ++bj)
; #pragma unroll
;             for (int n = 0; n < 2; ++n) {
;                 const int c = col0 + bj * HALF + 4 * n;
;                 const f32x4 bv = *(const f32x4*)(bias + c);
; #pragma unroll
;                 for (int ai = 0; ai < 2; ++ai)
; #pragma unroll
;                     for (int m = 0; m < 4; ++m) {
;                         const size_t row = (size_t)(row0 + ai * HALF + m * 16);
;                         const f32x4 v = acc[ai][bj][m][n] + bv;
;                         const u32x2 yv = *(const u32x2*)(YGS + row * 256 + c);
;                         const float y0 = __uint_as_float(yv.x << 16), y1 = __uint_as_float(yv.x & 0xffff0000u), y2 = __uint_as_float(yv.y << 16), y3 = __uint_as_float(yv.y & 0xffff0000u);
;                         u32x2 w; w.x = cvt_pk_bf16(y0 * sigm(v[0]), y1 * sigm(v[1])); w.y = cvt_pk_bf16(y2 * sigm(v[2]), y3 * sigm(v[3]));
;                         *(u32x2*)(MIX + row * 1024 + 256 + c) = w;
;                         if (m & 1) asm volatile("" ::: "memory");
;                     }
;             }
	v_pk_add_f32 v[116:117], v[116:117], v[128:129]
	v_pk_add_f32 v[118:119], v[118:119], v[130:131]
	v_pk_add_f32 v[84:85], v[84:85], v[208:209]
	v_pk_add_f32 v[86:87], v[86:87], v[210:211]
	v_mul_f32_e32 v116, 0xbfb8aa3b, v116
	v_mul_f32_e32 v117, 0xbfb8aa3b, v117
	v_mul_f32_e32 v118, 0xbfb8aa3b, v118
	v_mul_f32_e32 v119, 0xbfb8aa3b, v119
	v_mul_f32_e32 v84, 0xbfb8aa3b, v84
	v_mul_f32_e32 v85, 0xbfb8aa3b, v85
	v_mul_f32_e32 v86, 0xbfb8aa3b, v86
	v_mul_f32_e32 v87, 0xbfb8aa3b, v87
	v_exp_f32_e32 v116, v116
	v_exp_f32_e32 v117, v117
	v_exp_f32_e32 v118, v118
	v_exp_f32_e32 v119, v119
	v_exp_f32_e32 v84, v84
	v_exp_f32_e32 v85, v85
	v_exp_f32_e32 v86, v86
	v_exp_f32_e32 v87, v87
	v_add_f32_e32 v116, 1.0, v116
	v_add_f32_e32 v117, 1.0, v117
	v_add_f32_e32 v118, 1.0, v118
	v_add_f32_e32 v119, 1.0, v119
	v_add_f32_e32 v84, 1.0, v84
	v_add_f32_e32 v85, 1.0, v85
	v_add_f32_e32 v86, 1.0, v86
	v_add_f32_e32 v87, 1.0, v87
	v_rcp_f32_e32 v116, v116
	v_rcp_f32_e32 v117, v117
	v_rcp_f32_e32 v118, v118
	v_rcp_f32_e32 v119, v119
	v_rcp_f32_e32 v84, v84
	v_rcp_f32_e32 v85, v85
	v_rcp_f32_e32 v86, v86
	v_rcp_f32_e32 v87, v87
	v_lshlrev_b32_e32 v153, 16, v168
	v_and_b32_e32 v168, 0xffff0000, v168
	v_lshlrev_b32_e32 v155, 16, v169
	v_and_b32_e32 v169, 0xffff0000, v169
	v_mul_f32_e32 v116, v116, v153
	v_mul_f32_e32 v117, v117, v168
	v_mul_f32_e32 v118, v118, v155
	v_mul_f32_e32 v119, v119, v169
	v_lshlrev_b32_e32 v153, 16, v170
	v_and_b32_e32 v170, 0xffff0000, v170
	v_lshlrev_b32_e32 v155, 16, v171
	v_and_b32_e32 v171, 0xffff0000, v171
	v_mul_f32_e32 v84, v84, v153
	v_mul_f32_e32 v85, v85, v170
	v_mul_f32_e32 v86, v86, v155
	v_mul_f32_e32 v87, v87, v171
	v_cvt_pk_bf16_f32 v116, v116, v117
	v_cvt_pk_bf16_f32 v117, v118, v119
	v_cvt_pk_bf16_f32 v118, v84, v85
	v_cvt_pk_bf16_f32 v119, v86, v87
	v_or_b32_e32 v152, 32, v154
	v_lshlrev_b32_e32 v220, 11, v152
	v_lshl_add_u64 v[150:151], v[142:143], 0, v[220:221]
	global_store_dwordx4 v[150:151], v[116:119], off offset:512
	v_or_b32_e32 v152, 0x80, v154
	v_lshlrev_b32_e32 v220, 9, v152
	v_lshl_add_u64 v[148:149], v[140:141], 0, v[220:221]
	global_load_dwordx4 v[84:87], v[148:149], off offset:256
	s_waitcnt vmcnt(14)
	v_pk_add_f32 v[112:113], v[112:113], v[128:129]
	v_pk_add_f32 v[114:115], v[114:115], v[130:131]
	v_pk_add_f32 v[80:81], v[80:81], v[208:209]
	v_pk_add_f32 v[82:83], v[82:83], v[210:211]
	v_mul_f32_e32 v112, 0xbfb8aa3b, v112
	v_mul_f32_e32 v113, 0xbfb8aa3b, v113
	v_mul_f32_e32 v114, 0xbfb8aa3b, v114
	v_mul_f32_e32 v115, 0xbfb8aa3b, v115
	v_mul_f32_e32 v80, 0xbfb8aa3b, v80
	v_mul_f32_e32 v81, 0xbfb8aa3b, v81
	v_mul_f32_e32 v82, 0xbfb8aa3b, v82
	v_mul_f32_e32 v83, 0xbfb8aa3b, v83
	v_exp_f32_e32 v112, v112
	v_exp_f32_e32 v113, v113
	v_exp_f32_e32 v114, v114
	v_exp_f32_e32 v115, v115
	v_exp_f32_e32 v80, v80
	v_exp_f32_e32 v81, v81
	v_exp_f32_e32 v82, v82
	v_exp_f32_e32 v83, v83
	v_add_f32_e32 v112, 1.0, v112
	v_add_f32_e32 v113, 1.0, v113
	v_add_f32_e32 v114, 1.0, v114
	v_add_f32_e32 v115, 1.0, v115
	v_add_f32_e32 v80, 1.0, v80
	v_add_f32_e32 v81, 1.0, v81
	v_add_f32_e32 v82, 1.0, v82
	v_add_f32_e32 v83, 1.0, v83
	v_rcp_f32_e32 v112, v112
	v_rcp_f32_e32 v113, v113
	v_rcp_f32_e32 v114, v114
	v_rcp_f32_e32 v115, v115
	v_rcp_f32_e32 v80, v80
	v_rcp_f32_e32 v81, v81
	v_rcp_f32_e32 v82, v82
	v_rcp_f32_e32 v83, v83
	v_lshlrev_b32_e32 v153, 16, v172
	v_and_b32_e32 v172, 0xffff0000, v172
	v_lshlrev_b32_e32 v155, 16, v173
	v_and_b32_e32 v173, 0xffff0000, v173
	v_mul_f32_e32 v112, v112, v153
	v_mul_f32_e32 v113, v113, v172
	v_mul_f32_e32 v114, v114, v155
	v_mul_f32_e32 v115, v115, v173
	v_lshlrev_b32_e32 v153, 16, v174
	v_and_b32_e32 v174, 0xffff0000, v174
	v_lshlrev_b32_e32 v155, 16, v175
	v_and_b32_e32 v175, 0xffff0000, v175
	v_mul_f32_e32 v80, v80, v153
	v_mul_f32_e32 v81, v81, v174
	v_mul_f32_e32 v82, v82, v155
	v_mul_f32_e32 v83, v83, v175
	v_cvt_pk_bf16_f32 v112, v112, v113
	v_cvt_pk_bf16_f32 v113, v114, v115
	v_cvt_pk_bf16_f32 v114, v80, v81
	v_cvt_pk_bf16_f32 v115, v82, v83
	v_or_b32_e32 v152, 48, v154
	v_lshlrev_b32_e32 v220, 11, v152
	v_lshl_add_u64 v[150:151], v[142:143], 0, v[220:221]
	global_store_dwordx4 v[150:151], v[112:115], off offset:512
	v_or_b32_e32 v152, 0x90, v154
	v_lshlrev_b32_e32 v220, 9, v152
	v_lshl_add_u64 v[148:149], v[140:141], 0, v[220:221]
	global_load_dwordx4 v[80:83], v[148:149], off offset:256
	s_waitcnt vmcnt(15)
	v_pk_add_f32 v[108:109], v[108:109], v[128:129]
	v_pk_add_f32 v[110:111], v[110:111], v[130:131]
	v_pk_add_f32 v[76:77], v[76:77], v[208:209]
	v_pk_add_f32 v[78:79], v[78:79], v[210:211]
	v_mul_f32_e32 v108, 0xbfb8aa3b, v108
	v_mul_f32_e32 v109, 0xbfb8aa3b, v109
	v_mul_f32_e32 v110, 0xbfb8aa3b, v110
	v_mul_f32_e32 v111, 0xbfb8aa3b, v111
	v_mul_f32_e32 v76, 0xbfb8aa3b, v76
	v_mul_f32_e32 v77, 0xbfb8aa3b, v77
	v_mul_f32_e32 v78, 0xbfb8aa3b, v78
	v_mul_f32_e32 v79, 0xbfb8aa3b, v79
	v_exp_f32_e32 v108, v108
	v_exp_f32_e32 v109, v109
	v_exp_f32_e32 v110, v110
	v_exp_f32_e32 v111, v111
	v_exp_f32_e32 v76, v76
	v_exp_f32_e32 v77, v77
	v_exp_f32_e32 v78, v78
	v_exp_f32_e32 v79, v79
	v_add_f32_e32 v108, 1.0, v108
	v_add_f32_e32 v109, 1.0, v109
	v_add_f32_e32 v110, 1.0, v110
	v_add_f32_e32 v111, 1.0, v111
	v_add_f32_e32 v76, 1.0, v76
	v_add_f32_e32 v77, 1.0, v77
	v_add_f32_e32 v78, 1.0, v78
	v_add_f32_e32 v79, 1.0, v79
	v_rcp_f32_e32 v108, v108
	v_rcp_f32_e32 v109, v109
	v_rcp_f32_e32 v110, v110
	v_rcp_f32_e32 v111, v111
	v_rcp_f32_e32 v76, v76
	v_rcp_f32_e32 v77, v77
	v_rcp_f32_e32 v78, v78
	v_rcp_f32_e32 v79, v79
	v_lshlrev_b32_e32 v153, 16, v176
	v_and_b32_e32 v176, 0xffff0000, v176
	v_lshlrev_b32_e32 v155, 16, v177
	v_and_b32_e32 v177, 0xffff0000, v177
	v_mul_f32_e32 v108, v108, v153
	v_mul_f32_e32 v109, v109, v176
	v_mul_f32_e32 v110, v110, v155
	v_mul_f32_e32 v111, v111, v177
	v_lshlrev_b32_e32 v153, 16, v178
	v_and_b32_e32 v178, 0xffff0000, v178
	v_lshlrev_b32_e32 v155, 16, v179
	v_and_b32_e32 v179, 0xffff0000, v179
	v_mul_f32_e32 v76, v76, v153
	v_mul_f32_e32 v77, v77, v178
	v_mul_f32_e32 v78, v78, v155
	v_mul_f32_e32 v79, v79, v179
	v_cvt_pk_bf16_f32 v108, v108, v109
	v_cvt_pk_bf16_f32 v109, v110, v111
	v_cvt_pk_bf16_f32 v110, v76, v77
	v_cvt_pk_bf16_f32 v111, v78, v79
	v_or_b32_e32 v152, 0x80, v154
	v_lshlrev_b32_e32 v220, 11, v152
	v_lshl_add_u64 v[150:151], v[142:143], 0, v[220:221]
	global_store_dwordx4 v[150:151], v[108:111], off offset:512
	v_or_b32_e32 v152, 0xa0, v154
	v_lshlrev_b32_e32 v220, 9, v152
	v_lshl_add_u64 v[148:149], v[140:141], 0, v[220:221]
	global_load_dwordx4 v[76:79], v[148:149], off offset:256
	s_waitcnt vmcnt(16)
; __device__ __forceinline__ unsigned cvt_pk_bf16(float lo, float hi) { unsigned r; asm volatile("v_cvt_pk_bf16_f32 %0, %1, %2" : "=v"(r) : "v"(lo), "v"(hi)); return r; }
; __device__ __forceinline__ float sigm(float v) { return __builtin_amdgcn_rcpf(1.0f + __builtin_amdgcn_exp2f(-1.4426950408889634f * v)); }
;     __device__ __forceinline__ void operator()(const f32x4 (&acc)[2][2][4][2], const Unit& u, int wr, int wc, int fr, int fq) const {
;         typedef unsigned u32x2 __attribute__((ext_vector_type(2)));
;         const int row0 = u.pm * BM + wr * 64 + fr, col0 = wc * 32 + 8 * fq;
; #pragma unroll
;         for (int bj = 0; bj < 2; ++bj)
; #pragma unroll
;             for (int n = 0; n < 2; ++n) {
;                 const int c = col0 + bj * HALF + 4 * n;
;                 const f32x4 bv = *(const f32x4*)(bias + c);
; #pragma unroll
;                 for (int ai = 0; ai < 2; ++ai)
; #pragma unroll
;                     for (int m = 0; m < 4; ++m) {
;                         const size_t row = (size_t)(row0 + ai * HALF + m * 16);
;                         const f32x4 v = acc[ai][bj][m][n] + bv;
;                         const u32x2 yv = *(const u32x2*)(YGS + row * 256 + c);
;                         const float y0 = __uint_as_float(yv.x << 16), y1 = __uint_as_float(yv.x & 0xffff0000u), y2 = __uint_as_float(yv.y << 16), y3 = __uint_as_float(yv.y & 0xffff0000u);
;                         u32x2 w; w.x = cvt_pk_bf16(y0 * sigm(v[0]), y1 * sigm(v[1])); w.y = cvt_pk_bf16(y2 * sigm(v[2]), y3 * sigm(v[3]));
;                         *(u32x2*)(MIX + row * 1024 + 256 + c) = w;
;                         if (m & 1) asm volatile("" ::: "memory");
;                     }
;             }
	v_pk_add_f32 v[104:105], v[104:105], v[128:129]
	v_pk_add_f32 v[106:107], v[106:107], v[130:131]
	v_pk_add_f32 v[72:73], v[72:73], v[208:209]
	v_pk_add_f32 v[74:75], v[74:75], v[210:211]
	v_mul_f32_e32 v104, 0xbfb8aa3b, v104
	v_mul_f32_e32 v105, 0xbfb8aa3b, v105
	v_mul_f32_e32 v106, 0xbfb8aa3b, v106
	v_mul_f32_e32 v107, 0xbfb8aa3b, v107
	v_mul_f32_e32 v72, 0xbfb8aa3b, v72
	v_mul_f32_e32 v73, 0xbfb8aa3b, v73
	v_mul_f32_e32 v74, 0xbfb8aa3b, v74
	v_mul_f32_e32 v75, 0xbfb8aa3b, v75
	v_exp_f32_e32 v104, v104
	v_exp_f32_e32 v105, v105
	v_exp_f32_e32 v106, v106
	v_exp_f32_e32 v107, v107
	v_exp_f32_e32 v72, v72
	v_exp_f32_e32 v73, v73
	v_exp_f32_e32 v74, v74
	v_exp_f32_e32 v75, v75
	v_add_f32_e32 v104, 1.0, v104
	v_add_f32_e32 v105, 1.0, v105
	v_add_f32_e32 v106, 1.0, v106
	v_add_f32_e32 v107, 1.0, v107
	v_add_f32_e32 v72, 1.0, v72
	v_add_f32_e32 v73, 1.0, v73
	v_add_f32_e32 v74, 1.0, v74
	v_add_f32_e32 v75, 1.0, v75
	v_rcp_f32_e32 v104, v104
	v_rcp_f32_e32 v105, v105
	v_rcp_f32_e32 v106, v106
	v_rcp_f32_e32 v107, v107
	v_rcp_f32_e32 v72, v72
	v_rcp_f32_e32 v73, v73
	v_rcp_f32_e32 v74, v74
	v_rcp_f32_e32 v75, v75
	v_lshlrev_b32_e32 v153, 16, v180
	v_and_b32_e32 v180, 0xffff0000, v180
	v_lshlrev_b32_e32 v155, 16, v181
	v_and_b32_e32 v181, 0xffff0000, v181
	v_mul_f32_e32 v104, v104, v153
	v_mul_f32_e32 v105, v105, v180
	v_mul_f32_e32 v106, v106, v155
	v_mul_f32_e32 v107, v107, v181
	v_lshlrev_b32_e32 v153, 16, v182
	v_and_b32_e32 v182, 0xffff0000, v182
	v_lshlrev_b32_e32 v155, 16, v183
	v_and_b32_e32 v183, 0xffff0000, v183
	v_mul_f32_e32 v72, v72, v153
	v_mul_f32_e32 v73, v73, v182
	v_mul_f32_e32 v74, v74, v155
	v_mul_f32_e32 v75, v75, v183
	v_cvt_pk_bf16_f32 v104, v104, v105
	v_cvt_pk_bf16_f32 v105, v106, v107
	v_cvt_pk_bf16_f32 v106, v72, v73
	v_cvt_pk_bf16_f32 v107, v74, v75
	v_or_b32_e32 v152, 0x90, v154
	v_lshlrev_b32_e32 v220, 11, v152
	v_lshl_add_u64 v[150:151], v[142:143], 0, v[220:221]
	global_store_dwordx4 v[150:151], v[104:107], off offset:512
	v_or_b32_e32 v152, 0xb0, v154
	v_lshlrev_b32_e32 v220, 9, v152
	v_lshl_add_u64 v[148:149], v[140:141], 0, v[220:221]
	global_load_dwordx4 v[72:75], v[148:149], off offset:256
	s_waitcnt vmcnt(17)
	v_pk_add_f32 v[100:101], v[100:101], v[128:129]
	v_pk_add_f32 v[102:103], v[102:103], v[130:131]
	v_pk_add_f32 v[68:69], v[68:69], v[208:209]
	v_pk_add_f32 v[70:71], v[70:71], v[210:211]
	v_mul_f32_e32 v100, 0xbfb8aa3b, v100
	v_mul_f32_e32 v101, 0xbfb8aa3b, v101
	v_mul_f32_e32 v102, 0xbfb8aa3b, v102
	v_mul_f32_e32 v103, 0xbfb8aa3b, v103
	v_mul_f32_e32 v68, 0xbfb8aa3b, v68
	v_mul_f32_e32 v69, 0xbfb8aa3b, v69
	v_mul_f32_e32 v70, 0xbfb8aa3b, v70
	v_mul_f32_e32 v71, 0xbfb8aa3b, v71
	v_exp_f32_e32 v100, v100
	v_exp_f32_e32 v101, v101
	v_exp_f32_e32 v102, v102
	v_exp_f32_e32 v103, v103
	v_exp_f32_e32 v68, v68
	v_exp_f32_e32 v69, v69
	v_exp_f32_e32 v70, v70
	v_exp_f32_e32 v71, v71
	v_add_f32_e32 v100, 1.0, v100
	v_add_f32_e32 v101, 1.0, v101
	v_add_f32_e32 v102, 1.0, v102
	v_add_f32_e32 v103, 1.0, v103
	v_add_f32_e32 v68, 1.0, v68
	v_add_f32_e32 v69, 1.0, v69
	v_add_f32_e32 v70, 1.0, v70
	v_add_f32_e32 v71, 1.0, v71
	v_rcp_f32_e32 v100, v100
	v_rcp_f32_e32 v101, v101
	v_rcp_f32_e32 v102, v102
	v_rcp_f32_e32 v103, v103
	v_rcp_f32_e32 v68, v68
	v_rcp_f32_e32 v69, v69
	v_rcp_f32_e32 v70, v70
	v_rcp_f32_e32 v71, v71
	v_lshlrev_b32_e32 v153, 16, v184
	v_and_b32_e32 v184, 0xffff0000, v184
	v_lshlrev_b32_e32 v155, 16, v185
	v_and_b32_e32 v185, 0xffff0000, v185
	v_mul_f32_e32 v100, v100, v153
	v_mul_f32_e32 v101, v101, v184
	v_mul_f32_e32 v102, v102, v155
	v_mul_f32_e32 v103, v103, v185
	v_lshlrev_b32_e32 v153, 16, v186
	v_and_b32_e32 v186, 0xffff0000, v186
	v_lshlrev_b32_e32 v155, 16, v187
	v_and_b32_e32 v187, 0xffff0000, v187
	v_mul_f32_e32 v68, v68, v153
	v_mul_f32_e32 v69, v69, v186
	v_mul_f32_e32 v70, v70, v155
	v_mul_f32_e32 v71, v71, v187
	v_cvt_pk_bf16_f32 v100, v100, v101
	v_cvt_pk_bf16_f32 v101, v102, v103
	v_cvt_pk_bf16_f32 v102, v68, v69
	v_cvt_pk_bf16_f32 v103, v70, v71
	v_or_b32_e32 v152, 0xa0, v154
	v_lshlrev_b32_e32 v220, 11, v152
	v_lshl_add_u64 v[150:151], v[142:143], 0, v[220:221]
	global_store_dwordx4 v[150:151], v[100:103], off offset:512
	s_waitcnt vmcnt(17)
	v_pk_add_f32 v[96:97], v[96:97], v[128:129]
	v_pk_add_f32 v[98:99], v[98:99], v[130:131]
	v_pk_add_f32 v[64:65], v[64:65], v[208:209]
	v_pk_add_f32 v[66:67], v[66:67], v[210:211]
	v_mul_f32_e32 v96, 0xbfb8aa3b, v96
	v_mul_f32_e32 v97, 0xbfb8aa3b, v97
	v_mul_f32_e32 v98, 0xbfb8aa3b, v98
	v_mul_f32_e32 v99, 0xbfb8aa3b, v99
	v_mul_f32_e32 v64, 0xbfb8aa3b, v64
	v_mul_f32_e32 v65, 0xbfb8aa3b, v65
	v_mul_f32_e32 v66, 0xbfb8aa3b, v66
	v_mul_f32_e32 v67, 0xbfb8aa3b, v67
	v_exp_f32_e32 v96, v96
	v_exp_f32_e32 v97, v97
	v_exp_f32_e32 v98, v98
	v_exp_f32_e32 v99, v99
	v_exp_f32_e32 v64, v64
	v_exp_f32_e32 v65, v65
	v_exp_f32_e32 v66, v66
	v_exp_f32_e32 v67, v67
	v_add_f32_e32 v96, 1.0, v96
	v_add_f32_e32 v97, 1.0, v97
	v_add_f32_e32 v98, 1.0, v98
	v_add_f32_e32 v99, 1.0, v99
	v_add_f32_e32 v64, 1.0, v64
	v_add_f32_e32 v65, 1.0, v65
	v_add_f32_e32 v66, 1.0, v66
	v_add_f32_e32 v67, 1.0, v67
	v_rcp_f32_e32 v96, v96
	v_rcp_f32_e32 v97, v97
	v_rcp_f32_e32 v98, v98
	v_rcp_f32_e32 v99, v99
	v_rcp_f32_e32 v64, v64
	v_rcp_f32_e32 v65, v65
	v_rcp_f32_e32 v66, v66
	v_rcp_f32_e32 v67, v67
	v_lshlrev_b32_e32 v153, 16, v188
	v_and_b32_e32 v188, 0xffff0000, v188
	v_lshlrev_b32_e32 v155, 16, v189
	v_and_b32_e32 v189, 0xffff0000, v189
	v_mul_f32_e32 v96, v96, v153
	v_mul_f32_e32 v97, v97, v188
	v_mul_f32_e32 v98, v98, v155
	v_mul_f32_e32 v99, v99, v189
	v_lshlrev_b32_e32 v153, 16, v190
	v_and_b32_e32 v190, 0xffff0000, v190
	v_lshlrev_b32_e32 v155, 16, v191
	v_and_b32_e32 v191, 0xffff0000, v191
	v_mul_f32_e32 v64, v64, v153
	v_mul_f32_e32 v65, v65, v190
	v_mul_f32_e32 v66, v66, v155
	v_mul_f32_e32 v67, v67, v191
	v_cvt_pk_bf16_f32 v96, v96, v97
	v_cvt_pk_bf16_f32 v97, v98, v99
	v_cvt_pk_bf16_f32 v98, v64, v65
	v_cvt_pk_bf16_f32 v99, v66, v67
	v_or_b32_e32 v152, 0xb0, v154
	v_lshlrev_b32_e32 v220, 11, v152
	v_lshl_add_u64 v[150:151], v[142:143], 0, v[220:221]
	global_store_dwordx4 v[150:151], v[96:99], off offset:512
	s_waitcnt vmcnt(10)
; __device__ __forceinline__ unsigned cvt_pk_bf16(float lo, float hi) { unsigned r; asm volatile("v_cvt_pk_bf16_f32 %0, %1, %2" : "=v"(r) : "v"(lo), "v"(hi)); return r; }
; __device__ __forceinline__ float sigm(float v) { return __builtin_amdgcn_rcpf(1.0f + __builtin_amdgcn_exp2f(-1.4426950408889634f * v)); }
;     __device__ __forceinline__ void operator()(const f32x4 (&acc)[2][2][4][2], const Unit& u, int wr, int wc, int fr, int fq) const {
;         typedef unsigned u32x2 __attribute__((ext_vector_type(2)));
;         const int row0 = u.pm * BM + wr * 64 + fr, col0 = wc * 32 + 8 * fq;
; #pragma unroll
;         for (int bj = 0; bj < 2; ++bj)
; #pragma unroll
;             for (int n = 0; n < 2; ++n) {
;                 const int c = col0 + bj * HALF + 4 * n;
;                 const f32x4 bv = *(const f32x4*)(bias + c);
; #pragma unroll
;                 for (int ai = 0; ai < 2; ++ai)
; #pragma unroll
;                     for (int m = 0; m < 4; ++m) {
;                         const size_t row = (size_t)(row0 + ai * HALF + m * 16);
;                         const f32x4 v = acc[ai][bj][m][n] + bv;
;                         const u32x2 yv = *(const u32x2*)(YGS + row * 256 + c);
;                         const float y0 = __uint_as_float(yv.x << 16), y1 = __uint_as_float(yv.x & 0xffff0000u), y2 = __uint_as_float(yv.y << 16), y3 = __uint_as_float(yv.y & 0xffff0000u);
;                         u32x2 w; w.x = cvt_pk_bf16(y0 * sigm(v[0]), y1 * sigm(v[1])); w.y = cvt_pk_bf16(y2 * sigm(v[2]), y3 * sigm(v[3]));
;                         *(u32x2*)(MIX + row * 1024 + 256 + c) = w;
;                         if (m & 1) asm volatile("" ::: "memory");
;                     }
;             }
	v_pk_add_f32 v[60:61], v[60:61], v[92:93]
	v_pk_add_f32 v[62:63], v[62:63], v[94:95]
	v_pk_add_f32 v[28:29], v[28:29], v[88:89]
	v_pk_add_f32 v[30:31], v[30:31], v[90:91]
	v_mul_f32_e32 v60, 0xbfb8aa3b, v60
	v_mul_f32_e32 v61, 0xbfb8aa3b, v61
	v_mul_f32_e32 v62, 0xbfb8aa3b, v62
	v_mul_f32_e32 v63, 0xbfb8aa3b, v63
	v_mul_f32_e32 v28, 0xbfb8aa3b, v28
	v_mul_f32_e32 v29, 0xbfb8aa3b, v29
	v_mul_f32_e32 v30, 0xbfb8aa3b, v30
	v_mul_f32_e32 v31, 0xbfb8aa3b, v31
	v_exp_f32_e32 v60, v60
	v_exp_f32_e32 v61, v61
	v_exp_f32_e32 v62, v62
	v_exp_f32_e32 v63, v63
	v_exp_f32_e32 v28, v28
	v_exp_f32_e32 v29, v29
	v_exp_f32_e32 v30, v30
	v_exp_f32_e32 v31, v31
	v_add_f32_e32 v60, 1.0, v60
	v_add_f32_e32 v61, 1.0, v61
	v_add_f32_e32 v62, 1.0, v62
	v_add_f32_e32 v63, 1.0, v63
	v_add_f32_e32 v28, 1.0, v28
	v_add_f32_e32 v29, 1.0, v29
	v_add_f32_e32 v30, 1.0, v30
	v_add_f32_e32 v31, 1.0, v31
	v_rcp_f32_e32 v60, v60
	v_rcp_f32_e32 v61, v61
	v_rcp_f32_e32 v62, v62
	v_rcp_f32_e32 v63, v63
	v_rcp_f32_e32 v28, v28
	v_rcp_f32_e32 v29, v29
	v_rcp_f32_e32 v30, v30
	v_rcp_f32_e32 v31, v31
	v_lshlrev_b32_e32 v153, 16, v192
	v_and_b32_e32 v192, 0xffff0000, v192
	v_lshlrev_b32_e32 v155, 16, v193
	v_and_b32_e32 v193, 0xffff0000, v193
	v_mul_f32_e32 v60, v60, v153
	v_mul_f32_e32 v61, v61, v192
	v_mul_f32_e32 v62, v62, v155
	v_mul_f32_e32 v63, v63, v193
	v_lshlrev_b32_e32 v153, 16, v194
	v_and_b32_e32 v194, 0xffff0000, v194
	v_lshlrev_b32_e32 v155, 16, v195
	v_and_b32_e32 v195, 0xffff0000, v195
	v_mul_f32_e32 v28, v28, v153
	v_mul_f32_e32 v29, v29, v194
	v_mul_f32_e32 v30, v30, v155
	v_mul_f32_e32 v31, v31, v195
	v_cvt_pk_bf16_f32 v60, v60, v61
	v_cvt_pk_bf16_f32 v61, v62, v63
	v_cvt_pk_bf16_f32 v62, v28, v29
	v_cvt_pk_bf16_f32 v63, v30, v31
	v_lshlrev_b32_e32 v220, 11, v154
	v_lshl_add_u64 v[150:151], v[142:143], 0, v[220:221]
	global_store_dwordx4 v[150:151], v[60:63], off offset:768
	v_pk_add_f32 v[56:57], v[56:57], v[92:93]
	v_pk_add_f32 v[58:59], v[58:59], v[94:95]
	v_pk_add_f32 v[24:25], v[24:25], v[88:89]
	v_pk_add_f32 v[26:27], v[26:27], v[90:91]
	v_mul_f32_e32 v56, 0xbfb8aa3b, v56
	v_mul_f32_e32 v57, 0xbfb8aa3b, v57
	v_mul_f32_e32 v58, 0xbfb8aa3b, v58
	v_mul_f32_e32 v59, 0xbfb8aa3b, v59
	v_mul_f32_e32 v24, 0xbfb8aa3b, v24
	v_mul_f32_e32 v25, 0xbfb8aa3b, v25
	v_mul_f32_e32 v26, 0xbfb8aa3b, v26
	v_mul_f32_e32 v27, 0xbfb8aa3b, v27
	v_exp_f32_e32 v56, v56
	v_exp_f32_e32 v57, v57
	v_exp_f32_e32 v58, v58
	v_exp_f32_e32 v59, v59
	v_exp_f32_e32 v24, v24
	v_exp_f32_e32 v25, v25
	v_exp_f32_e32 v26, v26
	v_exp_f32_e32 v27, v27
	v_add_f32_e32 v56, 1.0, v56
	v_add_f32_e32 v57, 1.0, v57
	v_add_f32_e32 v58, 1.0, v58
	v_add_f32_e32 v59, 1.0, v59
	v_add_f32_e32 v24, 1.0, v24
	v_add_f32_e32 v25, 1.0, v25
	v_add_f32_e32 v26, 1.0, v26
	v_add_f32_e32 v27, 1.0, v27
	v_rcp_f32_e32 v56, v56
	v_rcp_f32_e32 v57, v57
	v_rcp_f32_e32 v58, v58
	v_rcp_f32_e32 v59, v59
	v_rcp_f32_e32 v24, v24
	v_rcp_f32_e32 v25, v25
	v_rcp_f32_e32 v26, v26
	v_rcp_f32_e32 v27, v27
	v_lshlrev_b32_e32 v153, 16, v196
	v_and_b32_e32 v196, 0xffff0000, v196
	v_lshlrev_b32_e32 v155, 16, v197
	v_and_b32_e32 v197, 0xffff0000, v197
	v_mul_f32_e32 v56, v56, v153
	v_mul_f32_e32 v57, v57, v196
	v_mul_f32_e32 v58, v58, v155
	v_mul_f32_e32 v59, v59, v197
	v_lshlrev_b32_e32 v153, 16, v198
	v_and_b32_e32 v198, 0xffff0000, v198
	v_lshlrev_b32_e32 v155, 16, v199
	v_and_b32_e32 v199, 0xffff0000, v199
	v_mul_f32_e32 v24, v24, v153
	v_mul_f32_e32 v25, v25, v198
	v_mul_f32_e32 v26, v26, v155
	v_mul_f32_e32 v27, v27, v199
	v_cvt_pk_bf16_f32 v56, v56, v57
	v_cvt_pk_bf16_f32 v57, v58, v59
	v_cvt_pk_bf16_f32 v58, v24, v25
	v_cvt_pk_bf16_f32 v59, v26, v27
	v_or_b32_e32 v152, 16, v154
	v_lshlrev_b32_e32 v220, 11, v152
	v_lshl_add_u64 v[150:151], v[142:143], 0, v[220:221]
	global_store_dwordx4 v[150:151], v[56:59], off offset:768
	v_pk_add_f32 v[52:53], v[52:53], v[92:93]
	v_pk_add_f32 v[54:55], v[54:55], v[94:95]
	v_pk_add_f32 v[20:21], v[20:21], v[88:89]
	v_pk_add_f32 v[22:23], v[22:23], v[90:91]
	v_mul_f32_e32 v52, 0xbfb8aa3b, v52
	v_mul_f32_e32 v53, 0xbfb8aa3b, v53
	v_mul_f32_e32 v54, 0xbfb8aa3b, v54
	v_mul_f32_e32 v55, 0xbfb8aa3b, v55
	v_mul_f32_e32 v20, 0xbfb8aa3b, v20
	v_mul_f32_e32 v21, 0xbfb8aa3b, v21
	v_mul_f32_e32 v22, 0xbfb8aa3b, v22
	v_mul_f32_e32 v23, 0xbfb8aa3b, v23
	v_exp_f32_e32 v52, v52
	v_exp_f32_e32 v53, v53
	v_exp_f32_e32 v54, v54
	v_exp_f32_e32 v55, v55
	v_exp_f32_e32 v20, v20
	v_exp_f32_e32 v21, v21
	v_exp_f32_e32 v22, v22
	v_exp_f32_e32 v23, v23
	v_add_f32_e32 v52, 1.0, v52
	v_add_f32_e32 v53, 1.0, v53
	v_add_f32_e32 v54, 1.0, v54
	v_add_f32_e32 v55, 1.0, v55
	v_add_f32_e32 v20, 1.0, v20
	v_add_f32_e32 v21, 1.0, v21
	v_add_f32_e32 v22, 1.0, v22
	v_add_f32_e32 v23, 1.0, v23
	v_rcp_f32_e32 v52, v52
	v_rcp_f32_e32 v53, v53
	v_rcp_f32_e32 v54, v54
	v_rcp_f32_e32 v55, v55
	v_rcp_f32_e32 v20, v20
	v_rcp_f32_e32 v21, v21
	v_rcp_f32_e32 v22, v22
	v_rcp_f32_e32 v23, v23
	v_lshlrev_b32_e32 v153, 16, v200
	v_and_b32_e32 v200, 0xffff0000, v200
	v_lshlrev_b32_e32 v155, 16, v201
	v_and_b32_e32 v201, 0xffff0000, v201
	v_mul_f32_e32 v52, v52, v153
	v_mul_f32_e32 v53, v53, v200
	v_mul_f32_e32 v54, v54, v155
	v_mul_f32_e32 v55, v55, v201
	v_lshlrev_b32_e32 v153, 16, v202
	v_and_b32_e32 v202, 0xffff0000, v202
	v_lshlrev_b32_e32 v155, 16, v203
	v_and_b32_e32 v203, 0xffff0000, v203
	v_mul_f32_e32 v20, v20, v153
	v_mul_f32_e32 v21, v21, v202
	v_mul_f32_e32 v22, v22, v155
	v_mul_f32_e32 v23, v23, v203
	v_cvt_pk_bf16_f32 v52, v52, v53
	v_cvt_pk_bf16_f32 v53, v54, v55
	v_cvt_pk_bf16_f32 v54, v20, v21
	v_cvt_pk_bf16_f32 v55, v22, v23
	v_or_b32_e32 v152, 32, v154
	v_lshlrev_b32_e32 v220, 11, v152
	v_lshl_add_u64 v[150:151], v[142:143], 0, v[220:221]
; __device__ __forceinline__ unsigned cvt_pk_bf16(float lo, float hi) { unsigned r; asm volatile("v_cvt_pk_bf16_f32 %0, %1, %2" : "=v"(r) : "v"(lo), "v"(hi)); return r; }
; __device__ __forceinline__ float sigm(float v) { return __builtin_amdgcn_rcpf(1.0f + __builtin_amdgcn_exp2f(-1.4426950408889634f * v)); }
;     __device__ __forceinline__ void operator()(const f32x4 (&acc)[2][2][4][2], const Unit& u, int wr, int wc, int fr, int fq) const {
;         typedef unsigned u32x2 __attribute__((ext_vector_type(2)));
;         const int row0 = u.pm * BM + wr * 64 + fr, col0 = wc * 32 + 8 * fq;
; #pragma unroll
;         for (int bj = 0; bj < 2; ++bj)
; #pragma unroll
;             for (int n = 0; n < 2; ++n) {
;                 const int c = col0 + bj * HALF + 4 * n;
;                 const f32x4 bv = *(const f32x4*)(bias + c);
; #pragma unroll
;                 for (int ai = 0; ai < 2; ++ai)
; #pragma unroll
;                     for (int m = 0; m < 4; ++m) {
;                         const size_t row = (size_t)(row0 + ai * HALF + m * 16);
;                         const f32x4 v = acc[ai][bj][m][n] + bv;
;                         const u32x2 yv = *(const u32x2*)(YGS + row * 256 + c);
;                         const float y0 = __uint_as_float(yv.x << 16), y1 = __uint_as_float(yv.x & 0xffff0000u), y2 = __uint_as_float(yv.y << 16), y3 = __uint_as_float(yv.y & 0xffff0000u);
;                         u32x2 w; w.x = cvt_pk_bf16(y0 * sigm(v[0]), y1 * sigm(v[1])); w.y = cvt_pk_bf16(y2 * sigm(v[2]), y3 * sigm(v[3]));
;                         *(u32x2*)(MIX + row * 1024 + 256 + c) = w;
;                         if (m & 1) asm volatile("" ::: "memory");
;                     }
;             }
	global_store_dwordx4 v[150:151], v[52:55], off offset:768
	v_pk_add_f32 v[48:49], v[48:49], v[92:93]
	v_pk_add_f32 v[50:51], v[50:51], v[94:95]
	v_pk_add_f32 v[16:17], v[16:17], v[88:89]
	v_pk_add_f32 v[18:19], v[18:19], v[90:91]
	v_mul_f32_e32 v48, 0xbfb8aa3b, v48
	v_mul_f32_e32 v49, 0xbfb8aa3b, v49
	v_mul_f32_e32 v50, 0xbfb8aa3b, v50
	v_mul_f32_e32 v51, 0xbfb8aa3b, v51
	v_mul_f32_e32 v16, 0xbfb8aa3b, v16
	v_mul_f32_e32 v17, 0xbfb8aa3b, v17
	v_mul_f32_e32 v18, 0xbfb8aa3b, v18
	v_mul_f32_e32 v19, 0xbfb8aa3b, v19
	v_exp_f32_e32 v48, v48
	v_exp_f32_e32 v49, v49
	v_exp_f32_e32 v50, v50
	v_exp_f32_e32 v51, v51
	v_exp_f32_e32 v16, v16
	v_exp_f32_e32 v17, v17
	v_exp_f32_e32 v18, v18
	v_exp_f32_e32 v19, v19
	v_add_f32_e32 v48, 1.0, v48
	v_add_f32_e32 v49, 1.0, v49
	v_add_f32_e32 v50, 1.0, v50
	v_add_f32_e32 v51, 1.0, v51
	v_add_f32_e32 v16, 1.0, v16
	v_add_f32_e32 v17, 1.0, v17
	v_add_f32_e32 v18, 1.0, v18
	v_add_f32_e32 v19, 1.0, v19
	v_rcp_f32_e32 v48, v48
	v_rcp_f32_e32 v49, v49
	v_rcp_f32_e32 v50, v50
	v_rcp_f32_e32 v51, v51
	v_rcp_f32_e32 v16, v16
	v_rcp_f32_e32 v17, v17
	v_rcp_f32_e32 v18, v18
	v_rcp_f32_e32 v19, v19
	v_lshlrev_b32_e32 v153, 16, v204
	v_and_b32_e32 v204, 0xffff0000, v204
	v_lshlrev_b32_e32 v155, 16, v205
	v_and_b32_e32 v205, 0xffff0000, v205
	v_mul_f32_e32 v48, v48, v153
	v_mul_f32_e32 v49, v49, v204
	v_mul_f32_e32 v50, v50, v155
	v_mul_f32_e32 v51, v51, v205
	v_lshlrev_b32_e32 v153, 16, v206
	v_and_b32_e32 v206, 0xffff0000, v206
	v_lshlrev_b32_e32 v155, 16, v207
	v_and_b32_e32 v207, 0xffff0000, v207
	v_mul_f32_e32 v16, v16, v153
	v_mul_f32_e32 v17, v17, v206
	v_mul_f32_e32 v18, v18, v155
	v_mul_f32_e32 v19, v19, v207
	v_cvt_pk_bf16_f32 v48, v48, v49
	v_cvt_pk_bf16_f32 v49, v50, v51
	v_cvt_pk_bf16_f32 v50, v16, v17
	v_cvt_pk_bf16_f32 v51, v18, v19
	v_or_b32_e32 v152, 48, v154
	v_lshlrev_b32_e32 v220, 11, v152
	v_lshl_add_u64 v[150:151], v[142:143], 0, v[220:221]
	global_store_dwordx4 v[150:151], v[48:51], off offset:768
	s_waitcnt vmcnt(12)
	v_pk_add_f32 v[44:45], v[44:45], v[92:93]
	v_pk_add_f32 v[46:47], v[46:47], v[94:95]
	v_pk_add_f32 v[12:13], v[12:13], v[88:89]
	v_pk_add_f32 v[14:15], v[14:15], v[90:91]
	v_mul_f32_e32 v44, 0xbfb8aa3b, v44
	v_mul_f32_e32 v45, 0xbfb8aa3b, v45
	v_mul_f32_e32 v46, 0xbfb8aa3b, v46
	v_mul_f32_e32 v47, 0xbfb8aa3b, v47
	v_mul_f32_e32 v12, 0xbfb8aa3b, v12
	v_mul_f32_e32 v13, 0xbfb8aa3b, v13
	v_mul_f32_e32 v14, 0xbfb8aa3b, v14
	v_mul_f32_e32 v15, 0xbfb8aa3b, v15
	v_exp_f32_e32 v44, v44
	v_exp_f32_e32 v45, v45
	v_exp_f32_e32 v46, v46
	v_exp_f32_e32 v47, v47
	v_exp_f32_e32 v12, v12
	v_exp_f32_e32 v13, v13
	v_exp_f32_e32 v14, v14
	v_exp_f32_e32 v15, v15
	v_add_f32_e32 v44, 1.0, v44
	v_add_f32_e32 v45, 1.0, v45
	v_add_f32_e32 v46, 1.0, v46
	v_add_f32_e32 v47, 1.0, v47
	v_add_f32_e32 v12, 1.0, v12
	v_add_f32_e32 v13, 1.0, v13
	v_add_f32_e32 v14, 1.0, v14
	v_add_f32_e32 v15, 1.0, v15
	v_rcp_f32_e32 v44, v44
	v_rcp_f32_e32 v45, v45
	v_rcp_f32_e32 v46, v46
	v_rcp_f32_e32 v47, v47
	v_rcp_f32_e32 v12, v12
	v_rcp_f32_e32 v13, v13
	v_rcp_f32_e32 v14, v14
	v_rcp_f32_e32 v15, v15
	v_lshlrev_b32_e32 v153, 16, v84
	v_and_b32_e32 v84, 0xffff0000, v84
	v_lshlrev_b32_e32 v155, 16, v85
	v_and_b32_e32 v85, 0xffff0000, v85
	v_mul_f32_e32 v44, v44, v153
	v_mul_f32_e32 v45, v45, v84
	v_mul_f32_e32 v46, v46, v155
	v_mul_f32_e32 v47, v47, v85
	v_lshlrev_b32_e32 v153, 16, v86
	v_and_b32_e32 v86, 0xffff0000, v86
	v_lshlrev_b32_e32 v155, 16, v87
	v_and_b32_e32 v87, 0xffff0000, v87
	v_mul_f32_e32 v12, v12, v153
	v_mul_f32_e32 v13, v13, v86
	v_mul_f32_e32 v14, v14, v155
	v_mul_f32_e32 v15, v15, v87
	v_cvt_pk_bf16_f32 v44, v44, v45
	v_cvt_pk_bf16_f32 v45, v46, v47
	v_cvt_pk_bf16_f32 v46, v12, v13
	v_cvt_pk_bf16_f32 v47, v14, v15
	v_or_b32_e32 v152, 0x80, v154
	v_lshlrev_b32_e32 v220, 11, v152
	v_lshl_add_u64 v[150:151], v[142:143], 0, v[220:221]
	global_store_dwordx4 v[150:151], v[44:47], off offset:768
	s_waitcnt vmcnt(11)
; __device__ __forceinline__ unsigned cvt_pk_bf16(float lo, float hi) { unsigned r; asm volatile("v_cvt_pk_bf16_f32 %0, %1, %2" : "=v"(r) : "v"(lo), "v"(hi)); return r; }
; __device__ __forceinline__ float sigm(float v) { return __builtin_amdgcn_rcpf(1.0f + __builtin_amdgcn_exp2f(-1.4426950408889634f * v)); }
;     __device__ __forceinline__ void operator()(const f32x4 (&acc)[2][2][4][2], const Unit& u, int wr, int wc, int fr, int fq) const {
;         typedef unsigned u32x2 __attribute__((ext_vector_type(2)));
;         const int row0 = u.pm * BM + wr * 64 + fr, col0 = wc * 32 + 8 * fq;
; #pragma unroll
;         for (int bj = 0; bj < 2; ++bj)
; #pragma unroll
;             for (int n = 0; n < 2; ++n) {
;                 const int c = col0 + bj * HALF + 4 * n;
;                 const f32x4 bv = *(const f32x4*)(bias + c);
; #pragma unroll
;                 for (int ai = 0; ai < 2; ++ai)
; #pragma unroll
;                     for (int m = 0; m < 4; ++m) {
;                         const size_t row = (size_t)(row0 + ai * HALF + m * 16);
;                         const f32x4 v = acc[ai][bj][m][n] + bv;
;                         const u32x2 yv = *(const u32x2*)(YGS + row * 256 + c);
;                         const float y0 = __uint_as_float(yv.x << 16), y1 = __uint_as_float(yv.x & 0xffff0000u), y2 = __uint_as_float(yv.y << 16), y3 = __uint_as_float(yv.y & 0xffff0000u);
;                         u32x2 w; w.x = cvt_pk_bf16(y0 * sigm(v[0]), y1 * sigm(v[1])); w.y = cvt_pk_bf16(y2 * sigm(v[2]), y3 * sigm(v[3]));
;                         *(u32x2*)(MIX + row * 1024 + 256 + c) = w;
;                         if (m & 1) asm volatile("" ::: "memory");
;                     }
;             }
	v_pk_add_f32 v[40:41], v[40:41], v[92:93]
	v_pk_add_f32 v[42:43], v[42:43], v[94:95]
	v_pk_add_f32 v[8:9], v[8:9], v[88:89]
	v_pk_add_f32 v[10:11], v[10:11], v[90:91]
	v_mul_f32_e32 v40, 0xbfb8aa3b, v40
	v_mul_f32_e32 v41, 0xbfb8aa3b, v41
	v_mul_f32_e32 v42, 0xbfb8aa3b, v42
	v_mul_f32_e32 v43, 0xbfb8aa3b, v43
	v_mul_f32_e32 v8, 0xbfb8aa3b, v8
	v_mul_f32_e32 v9, 0xbfb8aa3b, v9
	v_mul_f32_e32 v10, 0xbfb8aa3b, v10
	v_mul_f32_e32 v11, 0xbfb8aa3b, v11
	v_exp_f32_e32 v40, v40
	v_exp_f32_e32 v41, v41
	v_exp_f32_e32 v42, v42
	v_exp_f32_e32 v43, v43
	v_exp_f32_e32 v8, v8
	v_exp_f32_e32 v9, v9
	v_exp_f32_e32 v10, v10
	v_exp_f32_e32 v11, v11
	v_add_f32_e32 v40, 1.0, v40
	v_add_f32_e32 v41, 1.0, v41
	v_add_f32_e32 v42, 1.0, v42
	v_add_f32_e32 v43, 1.0, v43
	v_add_f32_e32 v8, 1.0, v8
	v_add_f32_e32 v9, 1.0, v9
	v_add_f32_e32 v10, 1.0, v10
	v_add_f32_e32 v11, 1.0, v11
	v_rcp_f32_e32 v40, v40
	v_rcp_f32_e32 v41, v41
	v_rcp_f32_e32 v42, v42
	v_rcp_f32_e32 v43, v43
	v_rcp_f32_e32 v8, v8
	v_rcp_f32_e32 v9, v9
	v_rcp_f32_e32 v10, v10
	v_rcp_f32_e32 v11, v11
	v_lshlrev_b32_e32 v153, 16, v80
	v_and_b32_e32 v80, 0xffff0000, v80
	v_lshlrev_b32_e32 v155, 16, v81
	v_and_b32_e32 v81, 0xffff0000, v81
	v_mul_f32_e32 v40, v40, v153
	v_mul_f32_e32 v41, v41, v80
	v_mul_f32_e32 v42, v42, v155
	v_mul_f32_e32 v43, v43, v81
	v_lshlrev_b32_e32 v153, 16, v82
	v_and_b32_e32 v82, 0xffff0000, v82
	v_lshlrev_b32_e32 v155, 16, v83
	v_and_b32_e32 v83, 0xffff0000, v83
	v_mul_f32_e32 v8, v8, v153
	v_mul_f32_e32 v9, v9, v82
	v_mul_f32_e32 v10, v10, v155
	v_mul_f32_e32 v11, v11, v83
	v_cvt_pk_bf16_f32 v40, v40, v41
	v_cvt_pk_bf16_f32 v41, v42, v43
	v_cvt_pk_bf16_f32 v42, v8, v9
	v_cvt_pk_bf16_f32 v43, v10, v11
	v_or_b32_e32 v152, 0x90, v154
	v_lshlrev_b32_e32 v220, 11, v152
	v_lshl_add_u64 v[150:151], v[142:143], 0, v[220:221]
	global_store_dwordx4 v[150:151], v[40:43], off offset:768
	s_waitcnt vmcnt(10)
	v_pk_add_f32 v[36:37], v[36:37], v[92:93]
	v_pk_add_f32 v[38:39], v[38:39], v[94:95]
	v_pk_add_f32 v[4:5], v[4:5], v[88:89]
	v_pk_add_f32 v[6:7], v[6:7], v[90:91]
	v_mul_f32_e32 v36, 0xbfb8aa3b, v36
	v_mul_f32_e32 v37, 0xbfb8aa3b, v37
	v_mul_f32_e32 v38, 0xbfb8aa3b, v38
	v_mul_f32_e32 v39, 0xbfb8aa3b, v39
	v_mul_f32_e32 v4, 0xbfb8aa3b, v4
	v_mul_f32_e32 v5, 0xbfb8aa3b, v5
	v_mul_f32_e32 v6, 0xbfb8aa3b, v6
	v_mul_f32_e32 v7, 0xbfb8aa3b, v7
	v_exp_f32_e32 v36, v36
	v_exp_f32_e32 v37, v37
	v_exp_f32_e32 v38, v38
	v_exp_f32_e32 v39, v39
	v_exp_f32_e32 v4, v4
	v_exp_f32_e32 v5, v5
	v_exp_f32_e32 v6, v6
	v_exp_f32_e32 v7, v7
	v_add_f32_e32 v36, 1.0, v36
	v_add_f32_e32 v37, 1.0, v37
	v_add_f32_e32 v38, 1.0, v38
	v_add_f32_e32 v39, 1.0, v39
	v_add_f32_e32 v4, 1.0, v4
	v_add_f32_e32 v5, 1.0, v5
	v_add_f32_e32 v6, 1.0, v6
	v_add_f32_e32 v7, 1.0, v7
	v_rcp_f32_e32 v36, v36
	v_rcp_f32_e32 v37, v37
	v_rcp_f32_e32 v38, v38
	v_rcp_f32_e32 v39, v39
	v_rcp_f32_e32 v4, v4
	v_rcp_f32_e32 v5, v5
	v_rcp_f32_e32 v6, v6
	v_rcp_f32_e32 v7, v7
	v_lshlrev_b32_e32 v153, 16, v76
	v_and_b32_e32 v76, 0xffff0000, v76
	v_lshlrev_b32_e32 v155, 16, v77
	v_and_b32_e32 v77, 0xffff0000, v77
	v_mul_f32_e32 v36, v36, v153
	v_mul_f32_e32 v37, v37, v76
	v_mul_f32_e32 v38, v38, v155
	v_mul_f32_e32 v39, v39, v77
	v_lshlrev_b32_e32 v153, 16, v78
	v_and_b32_e32 v78, 0xffff0000, v78
	v_lshlrev_b32_e32 v155, 16, v79
	v_and_b32_e32 v79, 0xffff0000, v79
	v_mul_f32_e32 v4, v4, v153
	v_mul_f32_e32 v5, v5, v78
	v_mul_f32_e32 v6, v6, v155
	v_mul_f32_e32 v7, v7, v79
	v_cvt_pk_bf16_f32 v36, v36, v37
	v_cvt_pk_bf16_f32 v37, v38, v39
	v_cvt_pk_bf16_f32 v38, v4, v5
	v_cvt_pk_bf16_f32 v39, v6, v7
	v_or_b32_e32 v152, 0xa0, v154
	v_lshlrev_b32_e32 v220, 11, v152
	v_lshl_add_u64 v[150:151], v[142:143], 0, v[220:221]
	global_store_dwordx4 v[150:151], v[36:39], off offset:768
	s_waitcnt vmcnt(9)
	v_pk_add_f32 v[32:33], v[32:33], v[92:93]
	v_pk_add_f32 v[34:35], v[34:35], v[94:95]
	v_pk_add_f32 v[0:1], v[0:1], v[88:89]
	v_pk_add_f32 v[2:3], v[2:3], v[90:91]
	v_mul_f32_e32 v32, 0xbfb8aa3b, v32
	v_mul_f32_e32 v33, 0xbfb8aa3b, v33
	v_mul_f32_e32 v34, 0xbfb8aa3b, v34
	v_mul_f32_e32 v35, 0xbfb8aa3b, v35
	v_mul_f32_e32 v0, 0xbfb8aa3b, v0
	v_mul_f32_e32 v1, 0xbfb8aa3b, v1
	v_mul_f32_e32 v2, 0xbfb8aa3b, v2
	v_mul_f32_e32 v3, 0xbfb8aa3b, v3
	v_exp_f32_e32 v32, v32
	v_exp_f32_e32 v33, v33
	v_exp_f32_e32 v34, v34
	v_exp_f32_e32 v35, v35
	v_exp_f32_e32 v0, v0
	v_exp_f32_e32 v1, v1
	v_exp_f32_e32 v2, v2
	v_exp_f32_e32 v3, v3
	v_add_f32_e32 v32, 1.0, v32
	v_add_f32_e32 v33, 1.0, v33
	v_add_f32_e32 v34, 1.0, v34
	v_add_f32_e32 v35, 1.0, v35
	v_add_f32_e32 v0, 1.0, v0
	v_add_f32_e32 v1, 1.0, v1
	v_add_f32_e32 v2, 1.0, v2
	v_add_f32_e32 v3, 1.0, v3
	v_rcp_f32_e32 v32, v32
	v_rcp_f32_e32 v33, v33
	v_rcp_f32_e32 v34, v34
	v_rcp_f32_e32 v35, v35
	v_rcp_f32_e32 v0, v0
	v_rcp_f32_e32 v1, v1
	v_rcp_f32_e32 v2, v2
	v_rcp_f32_e32 v3, v3
	v_lshlrev_b32_e32 v153, 16, v72
	v_and_b32_e32 v72, 0xffff0000, v72
	v_lshlrev_b32_e32 v155, 16, v73
	v_and_b32_e32 v73, 0xffff0000, v73
	v_mul_f32_e32 v32, v32, v153
	v_mul_f32_e32 v33, v33, v72
	v_mul_f32_e32 v34, v34, v155
	v_mul_f32_e32 v35, v35, v73
	v_lshlrev_b32_e32 v153, 16, v74
	v_and_b32_e32 v74, 0xffff0000, v74
	v_lshlrev_b32_e32 v155, 16, v75
	v_and_b32_e32 v75, 0xffff0000, v75
	v_mul_f32_e32 v0, v0, v153
	v_mul_f32_e32 v1, v1, v74
	v_mul_f32_e32 v2, v2, v155
	v_mul_f32_e32 v3, v3, v75
	v_cvt_pk_bf16_f32 v32, v32, v33
	v_cvt_pk_bf16_f32 v33, v34, v35
	v_cvt_pk_bf16_f32 v34, v0, v1
	v_cvt_pk_bf16_f32 v35, v2, v3
	v_or_b32_e32 v152, 0xb0, v154
	v_lshlrev_b32_e32 v220, 11, v152
	v_lshl_add_u64 v[150:151], v[142:143], 0, v[220:221]
	global_store_dwordx4 v[150:151], v[32:35], off offset:768
	s_cbranch_vccnz .LBB0_827
	s_andn2_b64 vcc, exec, s[24:25]
	s_cbranch_vccnz .LBB0_826
	s_barrier
	s_branch .LBB0_826
